# conv row reductions: intra-row xor hops via DPP (quad_perm/row_half_mirror/row_mirror) instead of ds_bpermute; on top of v81
# speedup vs baseline: 1.0063x; 1.0063x over previous
; #define GAS __attribute__((address_space(1)))
; __device__ __forceinline__ float bf_lo(unsigned w) { return __uint_as_float(w << 16); }
; __device__ __forceinline__ float bf_hi(unsigned w) { return __uint_as_float(w & 0xffff0000u); }
; #define CV_U(dst, xv, gv) do { dst[0] = bf_lo(xv.x) * bf_lo(gv.x); dst[1] = bf_hi(xv.x) * bf_hi(gv.x); dst[2] = bf_lo(xv.y) * bf_lo(gv.y); dst[3] = bf_hi(xv.y) * bf_hi(gv.y); \
;         dst[4] = bf_lo(xv.z) * bf_lo(gv.z); dst[5] = bf_hi(xv.z) * bf_hi(gv.z); dst[6] = bf_lo(xv.w) * bf_lo(gv.w); dst[7] = bf_hi(xv.w) * bf_hi(gv.w); } while (0)
; __device__ __forceinline__ float wave_sum(float v) {
;     ...
;     for (int o = 1; o < 64; o <<= 1) v += __shfl_xor(v, o);
; __device__ __forceinline__ void conv_unit(const bf16* PROJ, bf16* YMIX, const float* w_conv, const float* b_conv, const float* g_conv, int b, int c, int wave, int lane_in) {
;     ...
;         for (int r = 0; r < 10; ++r) { if (r >= 2 || s0 >= 2) { xa[r] = *(const GAS u32x4*)(rowp + (r - 2) * NPROJ + 1536); ga[r] = *(const GAS u32x4*)(rowp + (r - 2) * NPROJ + 2560); }
;             else { xa[r] = (u32x4){0u, 0u, 0u, 0u}; ga[r] = xa[r]; } }
; #pragma unroll
;         for (int r = 0; r < 8; ++r) gb[r] = __builtin_nontemporal_load((const GAS u32x4*)(rowp + r * NPROJ + 2048));
;     ...
;         float u0[8], u1[8];
;         CV_U(u0, xa[0], ga[0]); CV_U(u1, xa[1], ga[1]);
; #pragma unroll
;         for (int r = 0; r < 8; ++r) {
;             float u2[8]; CV_U(u2, xa[r + 2], ga[r + 2]);
;             const u32x4 gbv = gb[r];
;             float gbf[8] = {bf_lo(gbv.x), bf_hi(gbv.x), bf_lo(gbv.y), bf_hi(gbv.y), bf_lo(gbv.z), bf_hi(gbv.z), bf_lo(gbv.w), bf_hi(gbv.w)};
;             float y[8]; float ss = 0.f;
; #pragma unroll
;             for (int e = 0; e < 8; ++e) { y[e] = gbf[e] * (w0[e] * u0[e] + w1[e] * u1[e] + w2[e] * u2[e] + bc[e]); ss += y[e] * y[e]; }
;             const float rstd = 1.0f / sqrtf(wave_sum(ss) * (1.0f / 512.0f) + EPS);
.LBB0_549:
	v_add_co_u32_e32 v70, vcc, s41, v74
	global_load_dwordx4 v[62:65], v[74:75], off offset:3072
	s_nop 0
	v_addc_co_u32_e32 v71, vcc, 0, v75, vcc
	global_load_dwordx4 v[66:69], v[70:71], off offset:1024
	s_nop 0
	global_load_dwordx4 v[70:73], v[70:71], off nt
	s_waitcnt vmcnt(32)
	v_add_co_u32_e32 v86, vcc, s47, v74
	s_movk_i32 s4, 0x4000
	s_nop 0
	v_addc_co_u32_e32 v87, vcc, 0, v75, vcc
	v_add_co_u32_e32 v76, vcc, s39, v74
	s_waitcnt vmcnt(4)
	v_lshlrev_b32_e32 v88, 16, v53
	v_addc_co_u32_e32 v77, vcc, 0, v75, vcc
	v_add_co_u32_e32 v78, vcc, s4, v74
	s_movk_i32 s4, 0x5000
	s_nop 0
	v_addc_co_u32_e32 v79, vcc, 0, v75, vcc
	v_add_co_u32_e32 v80, vcc, s4, v74
	v_and_b32_e32 v89, 0xffff0000, v53
	s_nop 0
	v_addc_co_u32_e32 v81, vcc, 0, v75, vcc
	global_load_dwordx4 v[114:117], v[86:87], off offset:1024
	global_load_dwordx4 v[98:101], v[78:79], off offset:1024
	global_load_dwordx4 v[82:85], v[80:81], off offset:1024
	global_load_dwordx4 v[118:121], v[86:87], off offset:3072
	global_load_dwordx4 v[110:113], v[86:87], off offset:2048 nt
	s_waitcnt vmcnt(8)
	v_lshlrev_b32_e32 v94, 16, v57
	v_and_b32_e32 v95, 0xffff0000, v57
	v_lshlrev_b32_e32 v96, 16, v49
	v_and_b32_e32 v97, 0xffff0000, v49
	v_lshlrev_b32_e32 v102, 16, v61
	v_and_b32_e32 v103, 0xffff0000, v61
	v_lshlrev_b32_e32 v104, 16, v52
	v_and_b32_e32 v105, 0xffff0000, v52
	v_lshlrev_b32_e32 v52, 16, v56
	v_and_b32_e32 v53, 0xffff0000, v56
	v_lshlrev_b32_e32 v56, 16, v48
	v_and_b32_e32 v57, 0xffff0000, v48
	v_lshlrev_b32_e32 v48, 16, v60
	v_and_b32_e32 v49, 0xffff0000, v60
	v_lshlrev_b32_e32 v60, 16, v51
	v_and_b32_e32 v61, 0xffff0000, v51
	v_lshlrev_b32_e32 v106, 16, v55
	v_and_b32_e32 v107, 0xffff0000, v55
	v_pk_mul_f32 v[146:147], v[96:97], v[102:103]
	v_pk_mul_f32 v[144:145], v[56:57], v[48:49]
	v_pk_mul_f32 v[86:87], v[88:89], v[94:95]
	v_pk_mul_f32 v[52:53], v[104:105], v[52:53]
	v_pk_mul_f32 v[48:49], v[60:61], v[106:107]
	v_pk_mul_f32 v[56:57], v[36:37], v[146:147]
	v_pk_mul_f32 v[60:61], v[34:35], v[144:145]
	v_pk_fma_f32 v[56:57], v[32:33], v[86:87], v[56:57]
	v_pk_fma_f32 v[52:53], v[30:31], v[52:53], v[60:61]
	v_and_b32_e32 v51, 0xffff0000, v54
	v_and_b32_e32 v55, 0xffff0000, v46
	s_movk_i32 s4, 0x6000
	v_add_co_u32_e32 v90, vcc, s4, v74
	s_movk_i32 s4, 0x7000
	s_nop 0
	v_addc_co_u32_e32 v91, vcc, 0, v75, vcc
	v_add_co_u32_e32 v92, vcc, s4, v74
	s_mov_b32 s4, 0x8000
	s_nop 0
	v_addc_co_u32_e32 v93, vcc, 0, v75, vcc
	s_waitcnt vmcnt(7)
	v_lshlrev_b32_e32 v60, 16, v65
	v_and_b32_e32 v61, 0xffff0000, v65
	v_lshlrev_b32_e32 v86, 16, v64
	v_and_b32_e32 v87, 0xffff0000, v64
	s_waitcnt vmcnt(6)
	v_lshlrev_b32_e32 v64, 16, v69
	v_and_b32_e32 v65, 0xffff0000, v69
	v_pk_mul_f32 v[132:133], v[60:61], v[64:65]
	v_lshlrev_b32_e32 v60, 16, v47
	v_and_b32_e32 v61, 0xffff0000, v47
	v_lshlrev_b32_e32 v64, 16, v59
	v_and_b32_e32 v65, 0xffff0000, v59
	v_pk_mul_f32 v[148:149], v[60:61], v[64:65]
	v_lshlrev_b32_e32 v60, 16, v63
	v_and_b32_e32 v61, 0xffff0000, v63
	v_lshlrev_b32_e32 v64, 16, v67
	v_and_b32_e32 v65, 0xffff0000, v67
	v_pk_mul_f32 v[134:135], v[60:61], v[64:65]
	v_pk_mul_f32 v[64:65], v[20:21], v[148:149]
	s_waitcnt vmcnt(5)
	v_lshlrev_b32_e32 v60, 16, v71
	v_pk_fma_f32 v[48:49], v[16:17], v[48:49], v[64:65]
	v_and_b32_e32 v61, 0xffff0000, v71
	v_pk_fma_f32 v[48:49], v[24:25], v[134:135], v[48:49]
	v_and_b32_e32 v47, 0xffff0000, v58
	v_pk_add_f32 v[48:49], v[28:29], v[48:49]
	v_lshlrev_b32_e32 v94, 16, v68
	v_pk_mul_f32 v[150:151], v[48:49], v[60:61]
	v_lshlrev_b32_e32 v60, 16, v50
	v_and_b32_e32 v61, 0xffff0000, v50
	v_lshlrev_b32_e32 v50, 16, v54
	v_lshlrev_b32_e32 v54, 16, v46
	v_lshlrev_b32_e32 v46, 16, v58
	v_pk_mul_f32 v[152:153], v[54:55], v[46:47]
	v_lshlrev_b32_e32 v46, 16, v62
	v_and_b32_e32 v47, 0xffff0000, v62
	v_lshlrev_b32_e32 v54, 16, v66
	v_and_b32_e32 v55, 0xffff0000, v66
	v_pk_mul_f32 v[50:51], v[60:61], v[50:51]
	v_pk_mul_f32 v[140:141], v[46:47], v[54:55]
	v_pk_mul_f32 v[54:55], v[18:19], v[152:153]
	v_and_b32_e32 v95, 0xffff0000, v68
	v_pk_fma_f32 v[50:51], v[14:15], v[50:51], v[54:55]
	v_lshlrev_b32_e32 v46, 16, v70
	v_pk_fma_f32 v[50:51], v[22:23], v[140:141], v[50:51]
	v_and_b32_e32 v47, 0xffff0000, v70
	v_pk_add_f32 v[50:51], v[26:27], v[50:51]
	v_pk_mul_f32 v[130:131], v[86:87], v[94:95]
	v_pk_mul_f32 v[154:155], v[50:51], v[46:47]
	v_pk_fma_f32 v[52:53], v[38:39], v[130:131], v[52:53]
	v_pk_mul_f32 v[46:47], v[154:155], v[154:155]
	v_lshlrev_b32_e32 v68, 16, v72
	v_and_b32_e32 v69, 0xffff0000, v72
	v_pk_fma_f32 v[56:57], v[40:41], v[132:133], v[56:57]
	v_pk_add_f32 v[52:53], v[42:43], v[52:53]
	v_pk_mul_f32 v[48:49], v[150:151], v[150:151]
	v_add_f32_e32 v0, v46, v47
	v_lshlrev_b32_e32 v88, 16, v73
	v_and_b32_e32 v89, 0xffff0000, v73
	v_pk_add_f32 v[56:57], v[44:45], v[56:57]
	v_pk_mul_f32 v[138:139], v[52:53], v[68:69]
	v_add_f32_e32 v0, v48, v0
	v_pk_mul_f32 v[136:137], v[56:57], v[88:89]
	v_pk_mul_f32 v[56:57], v[138:139], v[138:139]
	v_add_f32_e32 v0, v49, v0
	v_add_f32_e32 v0, v56, v0
	v_pk_mul_f32 v[52:53], v[136:137], v[136:137]
	v_add_f32_e32 v0, v57, v0
	v_add_f32_e32 v0, v52, v0
	v_add_f32_e32 v0, v53, v0
	v_add_co_u32_e32 v50, vcc, s4, v74
	s_mov_b32 s4, 0x9000
	s_nop 0
	v_addc_co_u32_e32 v51, vcc, 0, v75, vcc
	s_waitcnt lgkmcnt(0)
	s_nop 1
	v_add_f32_dpp v0, v0, v0 quad_perm:[1,0,3,2] row_mask:0xf bank_mask:0xf
	v_add_co_u32_e32 v52, vcc, s4, v74
	s_mov_b32 s4, 0xa000
	s_nop 0
	v_addc_co_u32_e32 v53, vcc, 0, v75, vcc
	s_waitcnt lgkmcnt(0)
	s_nop 1
	v_add_f32_dpp v0, v0, v0 quad_perm:[2,3,0,1] row_mask:0xf bank_mask:0xf
	v_add_co_u32_e32 v54, vcc, s4, v74
	s_mov_b32 s4, 0xb000
	s_nop 0
	v_addc_co_u32_e32 v55, vcc, 0, v75, vcc
	s_waitcnt lgkmcnt(0)
; __device__ __forceinline__ unsigned cvtpk(float lo, float hi) { f32x2 v = {lo, hi}; bf16x2_t b = __builtin_convertvector(v, bf16x2_t); return __builtin_bit_cast(unsigned, b); }
; #define GAS __attribute__((address_space(1)))
; __device__ __forceinline__ float bf_lo(unsigned w) { return __uint_as_float(w << 16); }
; __device__ __forceinline__ float bf_hi(unsigned w) { return __uint_as_float(w & 0xffff0000u); }
; #define CV_U(dst, xv, gv) do { dst[0] = bf_lo(xv.x) * bf_lo(gv.x); dst[1] = bf_hi(xv.x) * bf_hi(gv.x); dst[2] = bf_lo(xv.y) * bf_lo(gv.y); dst[3] = bf_hi(xv.y) * bf_hi(gv.y); \
;         dst[4] = bf_lo(xv.z) * bf_lo(gv.z); dst[5] = bf_hi(xv.z) * bf_hi(gv.z); dst[6] = bf_lo(xv.w) * bf_lo(gv.w); dst[7] = bf_hi(xv.w) * bf_hi(gv.w); } while (0)
; __device__ __forceinline__ float wave_sum(float v) {
;     ...
;     for (int o = 1; o < 64; o <<= 1) v += __shfl_xor(v, o);
; __device__ __forceinline__ void conv_unit(const bf16* PROJ, bf16* YMIX, const float* w_conv, const float* b_conv, const float* g_conv, int b, int c, int wave, int lane_in) {
;     ...
;         for (int r = 0; r < 8; ++r) {
;             float u2[8]; CV_U(u2, xa[r + 2], ga[r + 2]);
;             const u32x4 gbv = gb[r];
;             float gbf[8] = {bf_lo(gbv.x), bf_hi(gbv.x), bf_lo(gbv.y), bf_hi(gbv.y), bf_lo(gbv.z), bf_hi(gbv.z), bf_lo(gbv.w), bf_hi(gbv.w)};
;             float y[8]; float ss = 0.f;
; #pragma unroll
;             for (int e = 0; e < 8; ++e) { y[e] = gbf[e] * (w0[e] * u0[e] + w1[e] * u1[e] + w2[e] * u2[e] + bc[e]); ss += y[e] * y[e]; }
;             const float rstd = 1.0f / sqrtf(wave_sum(ss) * (1.0f / 512.0f) + EPS);
;             u32x4 o;
;             o.x = cvtpk(y[0] * rstd * gc[0], y[1] * rstd * gc[1]); o.y = cvtpk(y[2] * rstd * gc[2], y[3] * rstd * gc[3]);
;             o.z = cvtpk(y[4] * rstd * gc[4], y[5] * rstd * gc[5]); o.w = cvtpk(y[6] * rstd * gc[6], y[7] * rstd * gc[7]);
;             *(GAS u32x4*)(YMIX + ((size_t)b * SEQ + s0 + r) * D + 512 + ch0) = o;
	s_nop 1
	v_add_f32_dpp v0, v0, v0 row_half_mirror row_mask:0xf bank_mask:0xf
	v_add_co_u32_e32 v142, vcc, s4, v74
	global_load_dwordx4 v[86:89], v[92:93], off offset:1024
	global_load_dwordx4 v[70:73], v[50:51], off offset:1024
	v_addc_co_u32_e32 v143, vcc, 0, v75, vcc
	s_waitcnt lgkmcnt(0)
	s_nop 1
	v_add_f32_dpp v0, v0, v0 row_mirror row_mask:0xf bank_mask:0xf
	ds_bpermute_b32 v5, v229, v0
	global_load_dwordx4 v[58:61], v[54:55], off offset:1024
	global_load_dwordx4 v[46:49], v[142:143], off offset:1024
	global_load_dwordx4 v[126:129], v[76:77], off offset:3072
	global_load_dwordx4 v[122:125], v[78:79], off nt
	global_load_dwordx4 v[106:109], v[80:81], off offset:3072
	global_load_dwordx4 v[102:105], v[80:81], off offset:2048 nt
	global_load_dwordx4 v[94:97], v[90:91], off offset:3072
	s_nop 0
	global_load_dwordx4 v[90:93], v[92:93], off nt
	s_nop 0
	global_load_dwordx4 v[78:81], v[50:51], off offset:3072
	global_load_dwordx4 v[74:77], v[50:51], off offset:2048 nt
	global_load_dwordx4 v[66:69], v[52:53], off offset:3072
	global_load_dwordx4 v[62:65], v[54:55], off nt
	s_nop 0
	global_load_dwordx4 v[54:57], v[142:143], off offset:3072
	global_load_dwordx4 v[50:53], v[142:143], off offset:2048 nt
	s_waitcnt lgkmcnt(0)
	v_add_f32_e32 v0, v0, v5
	ds_bpermute_b32 v5, v230, v0
	s_waitcnt vmcnt(17)
	v_lshlrev_b32_e32 v156, 16, v121
	v_and_b32_e32 v157, 0xffff0000, v121
	v_pk_mul_f32 v[158:159], v[36:37], v[132:133]
	s_waitcnt vmcnt(16)
	v_and_b32_e32 v121, 0xffff0000, v112
	s_waitcnt lgkmcnt(0)
	v_add_f32_e32 v0, v0, v5
	v_fmamk_f32 v0, v0, 0x3b000000, v220
	v_mul_f32_e32 v5, 0x4f800000, v0
	v_cmp_gt_f32_e32 vcc, s45, v0
	v_pk_fma_f32 v[146:147], v[32:33], v[146:147], v[158:159]
	v_lshlrev_b32_e32 v158, 16, v116
	v_cndmask_b32_e32 v0, v0, v5, vcc
	v_sqrt_f32_e32 v5, v0
	v_and_b32_e32 v159, 0xffff0000, v116
	v_lshlrev_b32_e32 v116, 16, v120
	v_pk_mul_f32 v[160:161], v[20:21], v[134:135]
	v_add_u32_e32 v142, -1, v5
	v_fma_f32 v143, -v142, v5, v0
	v_cmp_ge_f32_e64 s[4:5], 0, v143
	v_add_u32_e32 v143, 1, v5
	v_pk_fma_f32 v[148:149], v[16:17], v[148:149], v[160:161]
	v_cndmask_b32_e64 v142, v5, v142, s[4:5]
	v_fma_f32 v5, -v143, v5, v0
	v_cmp_lt_f32_e64 s[4:5], 0, v5
	v_lshlrev_b32_e32 v160, 16, v114
	v_and_b32_e32 v161, 0xffff0000, v114
	v_cndmask_b32_e64 v5, v142, v143, s[4:5]
	v_mul_f32_e32 v142, 0x37800000, v5
	v_cndmask_b32_e32 v5, v5, v142, vcc
	v_lshlrev_b32_e32 v142, 16, v117
	v_and_b32_e32 v143, 0xffff0000, v117
	v_pk_mul_f32 v[142:143], v[142:143], v[156:157]
	v_lshlrev_b32_e32 v156, 16, v113
	v_and_b32_e32 v157, 0xffff0000, v113
	v_and_b32_e32 v117, 0xffff0000, v120
	v_lshlrev_b32_e32 v120, 16, v112
	v_pk_mul_f32 v[112:113], v[34:35], v[130:131]
	v_pk_mul_f32 v[116:117], v[158:159], v[116:117]
	v_pk_fma_f32 v[112:113], v[30:31], v[144:145], v[112:113]
	v_lshlrev_b32_e32 v158, 16, v119
	v_pk_fma_f32 v[112:113], v[38:39], v[116:117], v[112:113]
	v_and_b32_e32 v159, 0xffff0000, v119
	v_pk_add_f32 v[112:113], v[42:43], v[112:113]
	v_lshlrev_b32_e32 v114, 16, v118
	v_pk_mul_f32 v[144:145], v[112:113], v[120:121]
	v_lshlrev_b32_e32 v112, 16, v115
	v_and_b32_e32 v113, 0xffff0000, v115
	v_pk_mul_f32 v[112:113], v[112:113], v[158:159]
	v_lshlrev_b32_e32 v158, 16, v111
	v_and_b32_e32 v159, 0xffff0000, v111
	v_and_b32_e32 v115, 0xffff0000, v118
	v_lshlrev_b32_e32 v118, 16, v110
	v_and_b32_e32 v119, 0xffff0000, v110
	v_pk_mul_f32 v[110:111], v[18:19], v[140:141]
	v_pk_mul_f32 v[114:115], v[160:161], v[114:115]
	v_pk_fma_f32 v[110:111], v[14:15], v[152:153], v[110:111]
	v_pk_fma_f32 v[148:149], v[24:25], v[112:113], v[148:149]
	v_pk_fma_f32 v[110:111], v[22:23], v[114:115], v[110:111]
	v_pk_add_f32 v[148:149], v[28:29], v[148:149]
	v_pk_add_f32 v[110:111], v[26:27], v[110:111]
	v_pk_mul_f32 v[158:159], v[148:149], v[158:159]
	v_pk_mul_f32 v[152:153], v[110:111], v[118:119]
	v_pk_mul_f32 v[148:149], v[158:159], v[158:159]
	v_pk_mul_f32 v[110:111], v[152:153], v[152:153]
	v_pk_fma_f32 v[146:147], v[40:41], v[142:143], v[146:147]
	v_add_f32_e32 v110, v110, v111
	v_add_f32_e32 v110, v148, v110
	v_pk_add_f32 v[146:147], v[44:45], v[146:147]
	v_pk_mul_f32 v[120:121], v[144:145], v[144:145]
	v_add_f32_e32 v110, v149, v110
	v_pk_mul_f32 v[146:147], v[146:147], v[156:157]
	v_add_f32_e32 v110, v120, v110
	v_pk_mul_f32 v[156:157], v[146:147], v[146:147]
	v_add_f32_e32 v110, v121, v110
	v_add_f32_e32 v110, v156, v110
	v_cmp_class_f32_e32 vcc, v0, v221
	v_add_f32_e32 v110, v157, v110
	v_cndmask_b32_e32 v0, v5, v0, vcc
	v_div_scale_f32 v5, s[4:5], v0, v0, 1.0
	v_rcp_f32_e32 v162, v5
	s_waitcnt lgkmcnt(0)
	s_nop 1
	v_add_f32_dpp v110, v110, v110 quad_perm:[1,0,3,2] row_mask:0xf bank_mask:0xf
	s_lshl_b64 s[4:5], s[6:7], 11
	v_fma_f32 v118, -v5, v162, 1.0
	v_fmac_f32_e32 v162, v118, v162
	v_div_scale_f32 v118, vcc, 1.0, v0, 1.0
	v_mul_f32_e32 v119, v118, v162
	v_fma_f32 v120, -v5, v119, v118
	v_fmac_f32_e32 v119, v120, v162
	v_fma_f32 v5, -v5, v119, v118
	s_waitcnt lgkmcnt(0)
	s_nop 1
	v_add_f32_dpp v118, v110, v110 quad_perm:[2,3,0,1] row_mask:0xf bank_mask:0xf
	v_div_fmas_f32 v5, v5, v162, v119
	v_div_fixup_f32 v0, v5, v0, 1.0
	v_pk_mul_f32 v[110:111], v[154:155], v[0:1] op_sel_hi:[1,0]
	s_add_u32 s4, s79, s4
	s_waitcnt lgkmcnt(0)
	s_nop 1
	v_add_f32_dpp v5, v118, v118 row_half_mirror row_mask:0xf bank_mask:0xf
	v_pk_mul_f32 v[110:111], v[10:11], v[110:111]
	s_addc_u32 s5, s80, s5
	v_cvt_pk_bf16_f32 v148, v110, v111
	v_pk_mul_f32 v[110:111], v[150:151], v[0:1] op_sel_hi:[1,0]
	s_waitcnt lgkmcnt(0)
	s_nop 1
	v_add_f32_dpp v5, v5, v5 row_mirror row_mask:0xf bank_mask:0xf
	ds_bpermute_b32 v118, v229, v5
	v_pk_mul_f32 v[110:111], v[12:13], v[110:111]
	v_lshl_add_u64 v[2:3], v[2:3], 1, s[4:5]
	v_cvt_pk_bf16_f32 v149, v110, v111
	v_pk_mul_f32 v[110:111], v[138:139], v[0:1] op_sel_hi:[1,0]
	s_waitcnt lgkmcnt(0)
; __device__ __forceinline__ unsigned cvtpk(float lo, float hi) { f32x2 v = {lo, hi}; bf16x2_t b = __builtin_convertvector(v, bf16x2_t); return __builtin_bit_cast(unsigned, b); }
; #define GAS __attribute__((address_space(1)))
; __device__ __forceinline__ float bf_lo(unsigned w) { return __uint_as_float(w << 16); }
; __device__ __forceinline__ float bf_hi(unsigned w) { return __uint_as_float(w & 0xffff0000u); }
; #define CV_U(dst, xv, gv) do { dst[0] = bf_lo(xv.x) * bf_lo(gv.x); dst[1] = bf_hi(xv.x) * bf_hi(gv.x); dst[2] = bf_lo(xv.y) * bf_lo(gv.y); dst[3] = bf_hi(xv.y) * bf_hi(gv.y); \
;         dst[4] = bf_lo(xv.z) * bf_lo(gv.z); dst[5] = bf_hi(xv.z) * bf_hi(gv.z); dst[6] = bf_lo(xv.w) * bf_lo(gv.w); dst[7] = bf_hi(xv.w) * bf_hi(gv.w); } while (0)
; __device__ __forceinline__ float wave_sum(float v) {
;     ...
;     for (int o = 1; o < 64; o <<= 1) v += __shfl_xor(v, o);
; __device__ __forceinline__ void conv_unit(const bf16* PROJ, bf16* YMIX, const float* w_conv, const float* b_conv, const float* g_conv, int b, int c, int wave, int lane_in) {
;     ...
;         for (int r = 0; r < 8; ++r) {
;             float u2[8]; CV_U(u2, xa[r + 2], ga[r + 2]);
;             const u32x4 gbv = gb[r];
;             float gbf[8] = {bf_lo(gbv.x), bf_hi(gbv.x), bf_lo(gbv.y), bf_hi(gbv.y), bf_lo(gbv.z), bf_hi(gbv.z), bf_lo(gbv.w), bf_hi(gbv.w)};
;             float y[8]; float ss = 0.f;
; #pragma unroll
;             for (int e = 0; e < 8; ++e) { y[e] = gbf[e] * (w0[e] * u0[e] + w1[e] * u1[e] + w2[e] * u2[e] + bc[e]); ss += y[e] * y[e]; }
;             const float rstd = 1.0f / sqrtf(wave_sum(ss) * (1.0f / 512.0f) + EPS);
;             u32x4 o;
;             o.x = cvtpk(y[0] * rstd * gc[0], y[1] * rstd * gc[1]); o.y = cvtpk(y[2] * rstd * gc[2], y[3] * rstd * gc[3]);
;             o.z = cvtpk(y[4] * rstd * gc[4], y[5] * rstd * gc[5]); o.w = cvtpk(y[6] * rstd * gc[6], y[7] * rstd * gc[7]);
;             *(GAS u32x4*)(YMIX + ((size_t)b * SEQ + s0 + r) * D + 512 + ch0) = o;
; #pragma unroll
;             for (int e = 0; e < 8; ++e) { u0[e] = u1[e]; u1[e] = u2[e]; }
	v_add_f32_e32 v5, v5, v118
	ds_bpermute_b32 v118, v230, v5
	v_pk_mul_f32 v[110:111], v[6:7], v[110:111]
	v_and_b32_e32 v119, 0xffff0000, v101
	v_cvt_pk_bf16_f32 v150, v110, v111
	v_pk_mul_f32 v[110:111], v[136:137], v[0:1] op_sel_hi:[1,0]
	s_waitcnt lgkmcnt(0)
	v_add_f32_e32 v0, v5, v118
	v_fmamk_f32 v0, v0, 0x3b000000, v220
	v_mul_f32_e32 v5, 0x4f800000, v0
	v_cmp_gt_f32_e32 vcc, s45, v0
	v_pk_mul_f32 v[110:111], v[8:9], v[110:111]
	v_lshlrev_b32_e32 v118, 16, v101
	v_cndmask_b32_e32 v0, v0, v5, vcc
	v_sqrt_f32_e32 v5, v0
	v_cvt_pk_bf16_f32 v151, v110, v111
	v_pk_mul_f32 v[120:121], v[36:37], v[142:143]
	s_waitcnt vmcnt(10)
	v_and_b32_e32 v101, 0xffff0000, v124
	v_add_u32_e32 v110, -1, v5
	v_fma_f32 v111, -v110, v5, v0
	v_cmp_ge_f32_e64 s[4:5], 0, v111
	v_add_u32_e32 v111, 1, v5
	v_pk_fma_f32 v[120:121], v[32:33], v[132:133], v[120:121]
	v_cndmask_b32_e64 v110, v5, v110, s[4:5]
	v_fma_f32 v5, -v111, v5, v0
	v_cmp_lt_f32_e64 s[4:5], 0, v5
	global_store_dwordx4 v[2:3], v[148:151], off offset:1024
	s_add_i32 s9, s9, 64
	v_cndmask_b32_e64 v5, v110, v111, s[4:5]
	v_mul_f32_e32 v110, 0x37800000, v5
	v_cndmask_b32_e32 v5, v5, v110, vcc
	v_lshlrev_b32_e32 v110, 16, v129
	v_and_b32_e32 v111, 0xffff0000, v129
	v_pk_mul_f32 v[110:111], v[110:111], v[118:119]
	v_lshlrev_b32_e32 v118, 16, v125
	v_pk_fma_f32 v[120:121], v[40:41], v[110:111], v[120:121]
	v_and_b32_e32 v119, 0xffff0000, v125
	v_pk_add_f32 v[120:121], v[44:45], v[120:121]
	v_and_b32_e32 v125, 0xffff0000, v99
	v_pk_mul_f32 v[132:133], v[120:121], v[118:119]
	v_lshlrev_b32_e32 v118, 16, v128
	v_and_b32_e32 v119, 0xffff0000, v128
	v_lshlrev_b32_e32 v120, 16, v100
	v_and_b32_e32 v121, 0xffff0000, v100
	v_pk_mul_f32 v[118:119], v[118:119], v[120:121]
	v_pk_mul_f32 v[120:121], v[34:35], v[116:117]
	v_lshlrev_b32_e32 v100, 16, v124
	v_pk_fma_f32 v[120:121], v[30:31], v[130:131], v[120:121]
	v_lshlrev_b32_e32 v124, 16, v99
	v_pk_fma_f32 v[120:121], v[38:39], v[118:119], v[120:121]
	v_pk_mul_f32 v[128:129], v[20:21], v[112:113]
	v_pk_add_f32 v[120:121], v[42:43], v[120:121]
	v_pk_fma_f32 v[128:129], v[16:17], v[134:135], v[128:129]
	v_pk_mul_f32 v[130:131], v[120:121], v[100:101]
	v_lshlrev_b32_e32 v120, 16, v127
	v_and_b32_e32 v121, 0xffff0000, v127
	v_pk_mul_f32 v[120:121], v[120:121], v[124:125]
	v_lshlrev_b32_e32 v124, 16, v123
	v_pk_fma_f32 v[128:129], v[24:25], v[120:121], v[128:129]
	v_and_b32_e32 v125, 0xffff0000, v123
	v_pk_add_f32 v[128:129], v[28:29], v[128:129]
	v_and_b32_e32 v127, 0xffff0000, v98
	v_pk_mul_f32 v[134:135], v[128:129], v[124:125]
	v_lshlrev_b32_e32 v124, 16, v126
	v_and_b32_e32 v125, 0xffff0000, v126
	v_lshlrev_b32_e32 v126, 16, v98
	v_lshlrev_b32_e32 v98, 16, v122
	v_and_b32_e32 v99, 0xffff0000, v122
	v_pk_mul_f32 v[122:123], v[18:19], v[114:115]
	v_pk_mul_f32 v[124:125], v[124:125], v[126:127]
	v_pk_fma_f32 v[122:123], v[14:15], v[140:141], v[122:123]
	v_cmp_class_f32_e32 vcc, v0, v221
	v_pk_fma_f32 v[122:123], v[22:23], v[124:125], v[122:123]
	v_pk_mul_f32 v[128:129], v[134:135], v[134:135]
	v_pk_add_f32 v[122:123], v[26:27], v[122:123]
	v_cndmask_b32_e32 v0, v5, v0, vcc
	v_pk_mul_f32 v[138:139], v[122:123], v[98:99]
	v_pk_mul_f32 v[100:101], v[130:131], v[130:131]
	v_pk_mul_f32 v[98:99], v[138:139], v[138:139]
	v_pk_mul_f32 v[136:137], v[132:133], v[132:133]
	v_add_f32_e32 v5, v98, v99
	v_add_f32_e32 v5, v128, v5
	v_add_f32_e32 v5, v129, v5
	v_add_f32_e32 v5, v100, v5
	v_add_f32_e32 v5, v101, v5
	v_add_f32_e32 v5, v136, v5
	v_add_f32_e32 v5, v137, v5
	v_div_scale_f32 v99, s[4:5], v0, v0, 1.0
	v_rcp_f32_e32 v100, v99
	v_pk_mul_f32 v[140:141], v[20:21], v[120:121]
	s_waitcnt lgkmcnt(0)
	s_nop 1
	v_add_f32_dpp v5, v5, v5 quad_perm:[1,0,3,2] row_mask:0xf bank_mask:0xf
	v_fma_f32 v101, -v99, v100, 1.0
	v_fmac_f32_e32 v100, v101, v100
	v_div_scale_f32 v101, vcc, 1.0, v0, 1.0
	s_waitcnt lgkmcnt(0)
	s_nop 1
	v_add_f32_dpp v5, v5, v5 quad_perm:[2,3,0,1] row_mask:0xf bank_mask:0xf
	v_mul_f32_e32 v122, v101, v100
	v_fma_f32 v123, -v99, v122, v101
	v_fmac_f32_e32 v122, v123, v100
	v_fma_f32 v99, -v99, v122, v101
	s_waitcnt lgkmcnt(0)
	s_nop 1
	v_add_f32_dpp v5, v5, v5 row_half_mirror row_mask:0xf bank_mask:0xf
	v_div_fmas_f32 v98, v99, v100, v122
	v_div_fixup_f32 v0, v98, v0, 1.0
	v_pk_mul_f32 v[98:99], v[152:153], v[0:1] op_sel_hi:[1,0]
	v_pk_mul_f32 v[122:123], v[36:37], v[110:111]
	s_waitcnt lgkmcnt(0)
	s_nop 1
	v_add_f32_dpp v5, v5, v5 row_mirror row_mask:0xf bank_mask:0xf
	ds_bpermute_b32 v100, v229, v5
	v_pk_mul_f32 v[98:99], v[10:11], v[98:99]
	s_waitcnt vmcnt(10)
	v_and_b32_e32 v101, 0xffff0000, v109
	v_cvt_pk_bf16_f32 v126, v98, v99
	v_pk_mul_f32 v[98:99], v[158:159], v[0:1] op_sel_hi:[1,0]
	s_waitcnt lgkmcnt(0)
	v_add_f32_e32 v5, v5, v100
	ds_bpermute_b32 v100, v230, v5
	v_pk_mul_f32 v[98:99], v[12:13], v[98:99]
	v_pk_fma_f32 v[122:123], v[32:33], v[142:143], v[122:123]
	v_cvt_pk_bf16_f32 v127, v98, v99
	v_pk_mul_f32 v[98:99], v[144:145], v[0:1] op_sel_hi:[1,0]
	s_waitcnt lgkmcnt(0)
	v_add_f32_e32 v5, v5, v100
	v_pk_mul_f32 v[98:99], v[6:7], v[98:99]
	v_fmamk_f32 v5, v5, 0x3b000000, v220
	v_cvt_pk_bf16_f32 v128, v98, v99
	v_mul_f32_e32 v98, 0x4f800000, v5
	v_cmp_gt_f32_e32 vcc, s45, v5
	v_pk_fma_f32 v[112:113], v[16:17], v[112:113], v[140:141]
	v_lshlrev_b32_e32 v140, 16, v82
	v_cndmask_b32_e32 v5, v5, v98, vcc
	v_sqrt_f32_e32 v100, v5
	v_pk_mul_f32 v[98:99], v[146:147], v[0:1] op_sel_hi:[1,0]
	v_and_b32_e32 v141, 0xffff0000, v82
	v_pk_mul_f32 v[98:99], v[8:9], v[98:99]
	v_add_u32_e32 v0, -1, v100
	v_cvt_pk_bf16_f32 v129, v98, v99
	v_fma_f32 v98, -v0, v100, v5
	v_cmp_ge_f32_e64 s[4:5], 0, v98
	v_add_u32_e32 v98, 1, v100
	v_fma_f32 v99, -v98, v100, v5
	v_cndmask_b32_e64 v0, v100, v0, s[4:5]
	v_cmp_lt_f32_e64 s[4:5], 0, v99
	v_and_b32_e32 v99, 0xffff0000, v85
	v_lshlrev_b32_e32 v100, 16, v109
	v_cndmask_b32_e64 v0, v0, v98, s[4:5]
	v_mul_f32_e32 v98, 0x37800000, v0
	v_cndmask_b32_e32 v0, v0, v98, vcc
	v_lshlrev_b32_e32 v98, 16, v85
	v_pk_mul_f32 v[98:99], v[98:99], v[100:101]
	s_waitcnt vmcnt(9)
; __device__ __forceinline__ unsigned cvtpk(float lo, float hi) { f32x2 v = {lo, hi}; bf16x2_t b = __builtin_convertvector(v, bf16x2_t); return __builtin_bit_cast(unsigned, b); }
; #define GAS __attribute__((address_space(1)))
; __device__ __forceinline__ float bf_lo(unsigned w) { return __uint_as_float(w << 16); }
; __device__ __forceinline__ float bf_hi(unsigned w) { return __uint_as_float(w & 0xffff0000u); }
; #define CV_U(dst, xv, gv) do { dst[0] = bf_lo(xv.x) * bf_lo(gv.x); dst[1] = bf_hi(xv.x) * bf_hi(gv.x); dst[2] = bf_lo(xv.y) * bf_lo(gv.y); dst[3] = bf_hi(xv.y) * bf_hi(gv.y); \
;         dst[4] = bf_lo(xv.z) * bf_lo(gv.z); dst[5] = bf_hi(xv.z) * bf_hi(gv.z); dst[6] = bf_lo(xv.w) * bf_lo(gv.w); dst[7] = bf_hi(xv.w) * bf_hi(gv.w); } while (0)
; __device__ __forceinline__ float wave_sum(float v) {
;     ...
;     for (int o = 1; o < 64; o <<= 1) v += __shfl_xor(v, o);
; __device__ __forceinline__ void conv_unit(const bf16* PROJ, bf16* YMIX, const float* w_conv, const float* b_conv, const float* g_conv, int b, int c, int wave, int lane_in) {
;     ...
;         for (int r = 0; r < 8; ++r) {
;             float u2[8]; CV_U(u2, xa[r + 2], ga[r + 2]);
;             const u32x4 gbv = gb[r];
;             float gbf[8] = {bf_lo(gbv.x), bf_hi(gbv.x), bf_lo(gbv.y), bf_hi(gbv.y), bf_lo(gbv.z), bf_hi(gbv.z), bf_lo(gbv.w), bf_hi(gbv.w)};
;             float y[8]; float ss = 0.f;
; #pragma unroll
;             for (int e = 0; e < 8; ++e) { y[e] = gbf[e] * (w0[e] * u0[e] + w1[e] * u1[e] + w2[e] * u2[e] + bc[e]); ss += y[e] * y[e]; }
;             const float rstd = 1.0f / sqrtf(wave_sum(ss) * (1.0f / 512.0f) + EPS);
;             u32x4 o;
;             o.x = cvtpk(y[0] * rstd * gc[0], y[1] * rstd * gc[1]); o.y = cvtpk(y[2] * rstd * gc[2], y[3] * rstd * gc[3]);
;             o.z = cvtpk(y[4] * rstd * gc[4], y[5] * rstd * gc[5]); o.w = cvtpk(y[6] * rstd * gc[6], y[7] * rstd * gc[7]);
;             *(GAS u32x4*)(YMIX + ((size_t)b * SEQ + s0 + r) * D + 512 + ch0) = o;
; #pragma unroll
;             for (int e = 0; e < 8; ++e) { u0[e] = u1[e]; u1[e] = u2[e]; }
	v_lshlrev_b32_e32 v100, 16, v105
	v_pk_fma_f32 v[122:123], v[40:41], v[98:99], v[122:123]
	v_and_b32_e32 v101, 0xffff0000, v105
	v_pk_add_f32 v[122:123], v[44:45], v[122:123]
	v_and_b32_e32 v85, 0xffff0000, v108
	v_pk_mul_f32 v[122:123], v[122:123], v[100:101]
	v_lshlrev_b32_e32 v100, 16, v84
	v_and_b32_e32 v101, 0xffff0000, v84
	v_lshlrev_b32_e32 v84, 16, v108
	v_pk_mul_f32 v[100:101], v[100:101], v[84:85]
	v_lshlrev_b32_e32 v84, 16, v104
	v_and_b32_e32 v85, 0xffff0000, v104
	v_pk_mul_f32 v[104:105], v[34:35], v[118:119]
	v_lshlrev_b32_e32 v82, 16, v106
	v_pk_fma_f32 v[104:105], v[30:31], v[116:117], v[104:105]
	v_lshlrev_b32_e32 v116, 16, v107
	v_pk_fma_f32 v[104:105], v[38:39], v[100:101], v[104:105]
	v_and_b32_e32 v117, 0xffff0000, v107
	v_pk_add_f32 v[104:105], v[42:43], v[104:105]
	v_cmp_class_f32_e32 vcc, v5, v221
	v_pk_mul_f32 v[108:109], v[104:105], v[84:85]
	v_lshlrev_b32_e32 v104, 16, v83
	v_and_b32_e32 v105, 0xffff0000, v83
	v_and_b32_e32 v83, 0xffff0000, v106
	v_pk_mul_f32 v[104:105], v[104:105], v[116:117]
	v_lshlrev_b32_e32 v116, 16, v103
	v_and_b32_e32 v117, 0xffff0000, v103
	v_pk_mul_f32 v[106:107], v[140:141], v[82:83]
	v_lshlrev_b32_e32 v82, 16, v102
	v_and_b32_e32 v83, 0xffff0000, v102
	v_pk_mul_f32 v[102:103], v[18:19], v[124:125]
	v_pk_fma_f32 v[112:113], v[24:25], v[104:105], v[112:113]
	v_pk_fma_f32 v[102:103], v[14:15], v[114:115], v[102:103]
	v_pk_add_f32 v[112:113], v[28:29], v[112:113]
	v_pk_fma_f32 v[102:103], v[22:23], v[106:107], v[102:103]
	v_pk_mul_f32 v[116:117], v[112:113], v[116:117]
	v_pk_add_f32 v[102:103], v[26:27], v[102:103]
	v_cndmask_b32_e32 v0, v0, v5, vcc
	v_pk_mul_f32 v[140:141], v[102:103], v[82:83]
	v_pk_mul_f32 v[112:113], v[116:117], v[116:117]
	v_pk_mul_f32 v[82:83], v[140:141], v[140:141]
	v_pk_mul_f32 v[84:85], v[108:109], v[108:109]
	v_add_f32_e32 v5, v82, v83
	v_add_f32_e32 v5, v112, v5
	v_add_f32_e32 v5, v113, v5
	v_add_f32_e32 v5, v84, v5
	v_pk_mul_f32 v[136:137], v[122:123], v[122:123]
	v_add_f32_e32 v5, v85, v5
	v_add_f32_e32 v5, v136, v5
	v_add_f32_e32 v5, v137, v5
	v_div_scale_f32 v83, s[4:5], v0, v0, 1.0
	v_rcp_f32_e32 v84, v83
	global_store_dwordx4 v[2:3], v[126:129], off offset:3072
	s_waitcnt lgkmcnt(0)
	s_nop 1
	v_add_f32_dpp v5, v5, v5 quad_perm:[1,0,3,2] row_mask:0xf bank_mask:0xf
	v_fma_f32 v85, -v83, v84, 1.0
	v_fmac_f32_e32 v84, v85, v84
	v_div_scale_f32 v85, vcc, 1.0, v0, 1.0
	s_waitcnt lgkmcnt(0)
	s_nop 1
	v_add_f32_dpp v5, v5, v5 quad_perm:[2,3,0,1] row_mask:0xf bank_mask:0xf
	v_mul_f32_e32 v102, v85, v84
	v_fma_f32 v103, -v83, v102, v85
	v_fmac_f32_e32 v102, v103, v84
	v_fma_f32 v83, -v83, v102, v85
	s_waitcnt lgkmcnt(0)
	s_nop 1
	v_add_f32_dpp v5, v5, v5 row_half_mirror row_mask:0xf bank_mask:0xf
	v_div_fmas_f32 v82, v83, v84, v102
	v_div_fixup_f32 v0, v82, v0, 1.0
	v_pk_mul_f32 v[82:83], v[138:139], v[0:1] op_sel_hi:[1,0]
	v_pk_mul_f32 v[102:103], v[36:37], v[98:99]
	s_waitcnt lgkmcnt(0)
	s_nop 1
	v_add_f32_dpp v5, v5, v5 row_mirror row_mask:0xf bank_mask:0xf
	ds_bpermute_b32 v84, v229, v5
	v_pk_mul_f32 v[82:83], v[10:11], v[82:83]
	v_and_b32_e32 v85, 0xffff0000, v89
	v_cvt_pk_bf16_f32 v112, v82, v83
	v_pk_mul_f32 v[82:83], v[134:135], v[0:1] op_sel_hi:[1,0]
	s_waitcnt lgkmcnt(0)
	v_add_f32_e32 v5, v5, v84
	ds_bpermute_b32 v84, v230, v5
	v_pk_mul_f32 v[82:83], v[12:13], v[82:83]
	v_pk_fma_f32 v[102:103], v[32:33], v[110:111], v[102:103]
	v_cvt_pk_bf16_f32 v113, v82, v83
	v_pk_mul_f32 v[82:83], v[130:131], v[0:1] op_sel_hi:[1,0]
	s_waitcnt lgkmcnt(0)
	v_add_f32_e32 v5, v5, v84
	v_pk_mul_f32 v[82:83], v[6:7], v[82:83]
	v_fmamk_f32 v5, v5, 0x3b000000, v220
	v_cvt_pk_bf16_f32 v114, v82, v83
	v_mul_f32_e32 v82, 0x4f800000, v5
	v_cmp_gt_f32_e32 vcc, s45, v5
	v_pk_mul_f32 v[126:127], v[20:21], v[104:105]
	s_nop 0
	v_cndmask_b32_e32 v5, v5, v82, vcc
	v_sqrt_f32_e32 v84, v5
	v_pk_mul_f32 v[82:83], v[132:133], v[0:1] op_sel_hi:[1,0]
	v_pk_fma_f32 v[120:121], v[16:17], v[120:121], v[126:127]
	v_pk_mul_f32 v[82:83], v[8:9], v[82:83]
	v_add_u32_e32 v0, -1, v84
	v_cvt_pk_bf16_f32 v115, v82, v83
	v_fma_f32 v82, -v0, v84, v5
	v_cmp_ge_f32_e64 s[4:5], 0, v82
	v_add_u32_e32 v82, 1, v84
	v_fma_f32 v83, -v82, v84, v5
	v_cndmask_b32_e64 v0, v84, v0, s[4:5]
	v_cmp_lt_f32_e64 s[4:5], 0, v83
	s_waitcnt vmcnt(9)
	v_and_b32_e32 v83, 0xffff0000, v97
	v_lshlrev_b32_e32 v84, 16, v89
	v_cndmask_b32_e64 v0, v0, v82, s[4:5]
	v_mul_f32_e32 v82, 0x37800000, v0
	v_cndmask_b32_e32 v0, v0, v82, vcc
	v_lshlrev_b32_e32 v82, 16, v97
	v_pk_mul_f32 v[82:83], v[82:83], v[84:85]
	s_waitcnt vmcnt(8)
	v_lshlrev_b32_e32 v84, 16, v93
	v_pk_fma_f32 v[102:103], v[40:41], v[82:83], v[102:103]
	v_and_b32_e32 v85, 0xffff0000, v93
	v_pk_add_f32 v[102:103], v[44:45], v[102:103]
	v_and_b32_e32 v97, 0xffff0000, v88
	v_pk_mul_f32 v[102:103], v[102:103], v[84:85]
	v_lshlrev_b32_e32 v84, 16, v96
	v_and_b32_e32 v85, 0xffff0000, v96
	v_lshlrev_b32_e32 v96, 16, v88
	v_lshlrev_b32_e32 v88, 16, v92
	v_and_b32_e32 v89, 0xffff0000, v92
	v_pk_mul_f32 v[92:93], v[34:35], v[100:101]
	v_pk_mul_f32 v[84:85], v[84:85], v[96:97]
	v_pk_fma_f32 v[92:93], v[30:31], v[118:119], v[92:93]
	v_lshlrev_b32_e32 v96, 16, v87
	v_pk_fma_f32 v[92:93], v[38:39], v[84:85], v[92:93]
	v_and_b32_e32 v97, 0xffff0000, v87
	v_pk_add_f32 v[92:93], v[42:43], v[92:93]
	v_lshlrev_b32_e32 v126, 16, v94
	v_pk_mul_f32 v[118:119], v[92:93], v[88:89]
	v_lshlrev_b32_e32 v88, 16, v95
	v_and_b32_e32 v89, 0xffff0000, v95
	v_and_b32_e32 v127, 0xffff0000, v94
	v_lshlrev_b32_e32 v94, 16, v86
	v_and_b32_e32 v95, 0xffff0000, v86
	v_pk_mul_f32 v[88:89], v[88:89], v[96:97]
	v_lshlrev_b32_e32 v96, 16, v91
	v_and_b32_e32 v97, 0xffff0000, v91
	v_pk_mul_f32 v[86:87], v[126:127], v[94:95]
	v_lshlrev_b32_e32 v94, 16, v90
	v_and_b32_e32 v95, 0xffff0000, v90
	v_pk_mul_f32 v[90:91], v[18:19], v[106:107]
	v_pk_fma_f32 v[120:121], v[24:25], v[88:89], v[120:121]
	v_pk_fma_f32 v[90:91], v[14:15], v[124:125], v[90:91]
	v_pk_add_f32 v[120:121], v[28:29], v[120:121]
	v_pk_fma_f32 v[90:91], v[22:23], v[86:87], v[90:91]
	v_pk_mul_f32 v[120:121], v[120:121], v[96:97]
	v_pk_add_f32 v[90:91], v[26:27], v[90:91]
	v_pk_mul_f32 v[96:97], v[120:121], v[120:121]
	v_pk_mul_f32 v[124:125], v[90:91], v[94:95]
	v_pk_mul_f32 v[92:93], v[118:119], v[118:119]
	v_pk_mul_f32 v[90:91], v[124:125], v[124:125]
	v_pk_mul_f32 v[110:111], v[102:103], v[102:103]
	v_add_f32_e32 v90, v90, v91
	v_add_f32_e32 v90, v96, v90
	v_add_f32_e32 v90, v97, v90
	v_add_f32_e32 v90, v92, v90
	v_add_f32_e32 v90, v93, v90
	v_add_f32_e32 v90, v110, v90
	v_add_f32_e32 v90, v111, v90
	v_cmp_class_f32_e32 vcc, v5, v221
	s_waitcnt lgkmcnt(0)
; __device__ __forceinline__ unsigned cvtpk(float lo, float hi) { f32x2 v = {lo, hi}; bf16x2_t b = __builtin_convertvector(v, bf16x2_t); return __builtin_bit_cast(unsigned, b); }
; #define GAS __attribute__((address_space(1)))
; __device__ __forceinline__ float bf_lo(unsigned w) { return __uint_as_float(w << 16); }
; __device__ __forceinline__ float bf_hi(unsigned w) { return __uint_as_float(w & 0xffff0000u); }
; #define CV_U(dst, xv, gv) do { dst[0] = bf_lo(xv.x) * bf_lo(gv.x); dst[1] = bf_hi(xv.x) * bf_hi(gv.x); dst[2] = bf_lo(xv.y) * bf_lo(gv.y); dst[3] = bf_hi(xv.y) * bf_hi(gv.y); \
;         dst[4] = bf_lo(xv.z) * bf_lo(gv.z); dst[5] = bf_hi(xv.z) * bf_hi(gv.z); dst[6] = bf_lo(xv.w) * bf_lo(gv.w); dst[7] = bf_hi(xv.w) * bf_hi(gv.w); } while (0)
; __device__ __forceinline__ float wave_sum(float v) {
;     ...
;     for (int o = 1; o < 64; o <<= 1) v += __shfl_xor(v, o);
; __device__ __forceinline__ void conv_unit(const bf16* PROJ, bf16* YMIX, const float* w_conv, const float* b_conv, const float* g_conv, int b, int c, int wave, int lane_in) {
;     ...
;         for (int r = 0; r < 8; ++r) {
;             float u2[8]; CV_U(u2, xa[r + 2], ga[r + 2]);
;             const u32x4 gbv = gb[r];
;             float gbf[8] = {bf_lo(gbv.x), bf_hi(gbv.x), bf_lo(gbv.y), bf_hi(gbv.y), bf_lo(gbv.z), bf_hi(gbv.z), bf_lo(gbv.w), bf_hi(gbv.w)};
;             float y[8]; float ss = 0.f;
; #pragma unroll
;             for (int e = 0; e < 8; ++e) { y[e] = gbf[e] * (w0[e] * u0[e] + w1[e] * u1[e] + w2[e] * u2[e] + bc[e]); ss += y[e] * y[e]; }
;             const float rstd = 1.0f / sqrtf(wave_sum(ss) * (1.0f / 512.0f) + EPS);
;             u32x4 o;
;             o.x = cvtpk(y[0] * rstd * gc[0], y[1] * rstd * gc[1]); o.y = cvtpk(y[2] * rstd * gc[2], y[3] * rstd * gc[3]);
;             o.z = cvtpk(y[4] * rstd * gc[4], y[5] * rstd * gc[5]); o.w = cvtpk(y[6] * rstd * gc[6], y[7] * rstd * gc[7]);
;             *(GAS u32x4*)(YMIX + ((size_t)b * SEQ + s0 + r) * D + 512 + ch0) = o;
; #pragma unroll
;             for (int e = 0; e < 8; ++e) { u0[e] = u1[e]; u1[e] = u2[e]; }
	s_nop 1
	v_add_f32_dpp v90, v90, v90 quad_perm:[1,0,3,2] row_mask:0xf bank_mask:0xf
	v_cndmask_b32_e32 v0, v0, v5, vcc
	v_div_scale_f32 v5, s[4:5], v0, v0, 1.0
	v_rcp_f32_e32 v92, v5
	s_waitcnt lgkmcnt(0)
	s_nop 1
	v_add_f32_dpp v90, v90, v90 quad_perm:[2,3,0,1] row_mask:0xf bank_mask:0xf
	v_add_co_u32_e32 v110, vcc, s41, v2
	v_fma_f32 v93, -v5, v92, 1.0
	s_nop 0
	v_addc_co_u32_e32 v111, vcc, 0, v3, vcc
	v_fmac_f32_e32 v92, v93, v92
	v_div_scale_f32 v93, vcc, 1.0, v0, 1.0
	s_waitcnt lgkmcnt(0)
	s_nop 1
	v_add_f32_dpp v90, v90, v90 row_half_mirror row_mask:0xf bank_mask:0xf
	v_mul_f32_e32 v94, v93, v92
	v_fma_f32 v95, -v5, v94, v93
	v_fmac_f32_e32 v94, v95, v92
	v_fma_f32 v5, -v5, v94, v93
	v_div_fmas_f32 v5, v5, v92, v94
	v_div_fixup_f32 v0, v5, v0, 1.0
	s_waitcnt lgkmcnt(0)
	s_nop 1
	v_add_f32_dpp v5, v90, v90 row_mirror row_mask:0xf bank_mask:0xf
	ds_bpermute_b32 v92, v229, v5
	v_pk_mul_f32 v[90:91], v[140:141], v[0:1] op_sel_hi:[1,0]
	global_store_dwordx4 v[110:111], v[112:115], off offset:1024
	v_pk_mul_f32 v[90:91], v[10:11], v[90:91]
	s_waitcnt vmcnt(8)
	v_and_b32_e32 v93, 0xffff0000, v81
	s_waitcnt lgkmcnt(0)
	v_add_f32_e32 v5, v5, v92
	ds_bpermute_b32 v92, v230, v5
	v_cvt_pk_bf16_f32 v94, v90, v91
	v_pk_mul_f32 v[90:91], v[116:117], v[0:1] op_sel_hi:[1,0]
	v_pk_mul_f32 v[112:113], v[36:37], v[82:83]
	v_pk_mul_f32 v[90:91], v[12:13], v[90:91]
	s_waitcnt lgkmcnt(0)
	v_add_f32_e32 v5, v5, v92
	v_fmamk_f32 v5, v5, 0x3b000000, v220
	v_mul_f32_e32 v92, 0x4f800000, v5
	v_cmp_gt_f32_e32 vcc, s45, v5
	v_cvt_pk_bf16_f32 v95, v90, v91
	v_pk_mul_f32 v[90:91], v[108:109], v[0:1] op_sel_hi:[1,0]
	v_cndmask_b32_e32 v5, v5, v92, vcc
	v_sqrt_f32_e32 v92, v5
	v_pk_mul_f32 v[90:91], v[6:7], v[90:91]
	v_pk_fma_f32 v[98:99], v[32:33], v[98:99], v[112:113]
	v_cvt_pk_bf16_f32 v96, v90, v91
	v_pk_mul_f32 v[90:91], v[122:123], v[0:1] op_sel_hi:[1,0]
	v_add_u32_e32 v0, -1, v92
	v_pk_mul_f32 v[108:109], v[8:9], v[90:91]
	v_fma_f32 v90, -v0, v92, v5
	v_cmp_ge_f32_e64 s[4:5], 0, v90
	v_add_u32_e32 v90, 1, v92
	v_fma_f32 v91, -v90, v92, v5
	v_cndmask_b32_e64 v0, v92, v0, s[4:5]
	v_cmp_lt_f32_e64 s[4:5], 0, v91
	v_and_b32_e32 v91, 0xffff0000, v73
	v_lshlrev_b32_e32 v92, 16, v81
	v_cndmask_b32_e64 v0, v0, v90, s[4:5]
	v_mul_f32_e32 v90, 0x37800000, v0
	v_cndmask_b32_e32 v0, v0, v90, vcc
	v_lshlrev_b32_e32 v90, 16, v73
	v_pk_mul_f32 v[90:91], v[90:91], v[92:93]
	s_waitcnt vmcnt(7)
	v_lshlrev_b32_e32 v92, 16, v77
	v_and_b32_e32 v93, 0xffff0000, v77
	v_lshlrev_b32_e32 v112, 16, v72
	v_and_b32_e32 v113, 0xffff0000, v72
	v_lshlrev_b32_e32 v72, 16, v80
	v_and_b32_e32 v73, 0xffff0000, v80
	v_lshlrev_b32_e32 v80, 16, v76
	v_and_b32_e32 v81, 0xffff0000, v76
	v_pk_mul_f32 v[76:77], v[34:35], v[84:85]
	v_pk_mul_f32 v[72:73], v[112:113], v[72:73]
	v_pk_fma_f32 v[76:77], v[30:31], v[100:101], v[76:77]
	v_lshlrev_b32_e32 v112, 16, v79
	v_pk_fma_f32 v[76:77], v[38:39], v[72:73], v[76:77]
	v_and_b32_e32 v113, 0xffff0000, v79
	v_pk_add_f32 v[76:77], v[42:43], v[76:77]
	v_pk_mul_f32 v[114:115], v[20:21], v[88:89]
	v_pk_mul_f32 v[80:81], v[76:77], v[80:81]
	v_lshlrev_b32_e32 v76, 16, v71
	v_and_b32_e32 v77, 0xffff0000, v71
	v_pk_mul_f32 v[76:77], v[76:77], v[112:113]
	v_lshlrev_b32_e32 v112, 16, v75
	v_and_b32_e32 v113, 0xffff0000, v75
	v_pk_fma_f32 v[104:105], v[16:17], v[104:105], v[114:115]
	v_lshlrev_b32_e32 v114, 16, v70
	v_and_b32_e32 v115, 0xffff0000, v70
	v_lshlrev_b32_e32 v70, 16, v78
	v_and_b32_e32 v71, 0xffff0000, v78
	v_lshlrev_b32_e32 v78, 16, v74
	v_and_b32_e32 v79, 0xffff0000, v74
	v_pk_mul_f32 v[74:75], v[18:19], v[86:87]
	v_pk_mul_f32 v[70:71], v[114:115], v[70:71]
	v_pk_fma_f32 v[74:75], v[14:15], v[106:107], v[74:75]
	v_pk_fma_f32 v[104:105], v[24:25], v[76:77], v[104:105]
	v_pk_fma_f32 v[74:75], v[22:23], v[70:71], v[74:75]
	v_pk_add_f32 v[104:105], v[28:29], v[104:105]
	v_pk_add_f32 v[74:75], v[26:27], v[74:75]
	v_pk_mul_f32 v[104:105], v[104:105], v[112:113]
	v_pk_mul_f32 v[106:107], v[74:75], v[78:79]
	v_pk_mul_f32 v[112:113], v[104:105], v[104:105]
	v_pk_mul_f32 v[74:75], v[106:107], v[106:107]
	v_pk_fma_f32 v[98:99], v[40:41], v[90:91], v[98:99]
	v_add_f32_e32 v74, v74, v75
	v_add_f32_e32 v74, v112, v74
	v_pk_add_f32 v[98:99], v[44:45], v[98:99]
	v_pk_mul_f32 v[100:101], v[80:81], v[80:81]
	v_add_f32_e32 v74, v113, v74
	v_pk_mul_f32 v[92:93], v[98:99], v[92:93]
	v_add_f32_e32 v74, v100, v74
	v_pk_mul_f32 v[98:99], v[92:93], v[92:93]
	v_add_f32_e32 v74, v101, v74
	v_add_f32_e32 v74, v98, v74
	v_add_f32_e32 v74, v99, v74
	v_cmp_class_f32_e32 vcc, v5, v221
	v_cvt_pk_bf16_f32 v97, v108, v109
	global_store_dwordx4 v[110:111], v[94:97], off offset:3072
	v_cndmask_b32_e32 v0, v0, v5, vcc
	v_div_scale_f32 v5, s[4:5], v0, v0, 1.0
	s_waitcnt lgkmcnt(0)
	s_nop 1
	v_add_f32_dpp v74, v74, v74 quad_perm:[1,0,3,2] row_mask:0xf bank_mask:0xf
	v_rcp_f32_e32 v116, v5
	v_lshlrev_b32_e32 v98, 16, v61
	v_and_b32_e32 v99, 0xffff0000, v61
	v_fma_f32 v78, -v5, v116, 1.0
	v_fmac_f32_e32 v116, v78, v116
	v_div_scale_f32 v78, vcc, 1.0, v0, 1.0
	s_waitcnt lgkmcnt(0)
	s_nop 1
	v_add_f32_dpp v74, v74, v74 quad_perm:[2,3,0,1] row_mask:0xf bank_mask:0xf
	v_mul_f32_e32 v79, v78, v116
	v_fma_f32 v94, -v5, v79, v78
	v_fmac_f32_e32 v79, v94, v116
	v_fma_f32 v5, -v5, v79, v78
	v_div_fmas_f32 v5, v5, v116, v79
	v_div_fixup_f32 v0, v5, v0, 1.0
	s_waitcnt lgkmcnt(0)
	s_nop 1
	v_add_f32_dpp v5, v74, v74 row_half_mirror row_mask:0xf bank_mask:0xf
	v_pk_mul_f32 v[74:75], v[124:125], v[0:1] op_sel_hi:[1,0]
	v_pk_mul_f32 v[100:101], v[36:37], v[90:91]
	v_pk_mul_f32 v[74:75], v[10:11], v[74:75]
	v_pk_fma_f32 v[82:83], v[32:33], v[82:83], v[100:101]
	s_waitcnt lgkmcnt(0)
; __device__ __forceinline__ unsigned cvtpk(float lo, float hi) { f32x2 v = {lo, hi}; bf16x2_t b = __builtin_convertvector(v, bf16x2_t); return __builtin_bit_cast(unsigned, b); }
; #define GAS __attribute__((address_space(1)))
; __device__ __forceinline__ float bf_lo(unsigned w) { return __uint_as_float(w << 16); }
; __device__ __forceinline__ float bf_hi(unsigned w) { return __uint_as_float(w & 0xffff0000u); }
; #define CV_U(dst, xv, gv) do { dst[0] = bf_lo(xv.x) * bf_lo(gv.x); dst[1] = bf_hi(xv.x) * bf_hi(gv.x); dst[2] = bf_lo(xv.y) * bf_lo(gv.y); dst[3] = bf_hi(xv.y) * bf_hi(gv.y); \
;         dst[4] = bf_lo(xv.z) * bf_lo(gv.z); dst[5] = bf_hi(xv.z) * bf_hi(gv.z); dst[6] = bf_lo(xv.w) * bf_lo(gv.w); dst[7] = bf_hi(xv.w) * bf_hi(gv.w); } while (0)
; __device__ __forceinline__ float wave_sum(float v) {
;     ...
;     for (int o = 1; o < 64; o <<= 1) v += __shfl_xor(v, o);
; __device__ __forceinline__ void conv_unit(const bf16* PROJ, bf16* YMIX, const float* w_conv, const float* b_conv, const float* g_conv, int b, int c, int wave, int lane_in) {
;     ...
;         for (int r = 0; r < 8; ++r) {
;             float u2[8]; CV_U(u2, xa[r + 2], ga[r + 2]);
;             const u32x4 gbv = gb[r];
;             float gbf[8] = {bf_lo(gbv.x), bf_hi(gbv.x), bf_lo(gbv.y), bf_hi(gbv.y), bf_lo(gbv.z), bf_hi(gbv.z), bf_lo(gbv.w), bf_hi(gbv.w)};
;             float y[8]; float ss = 0.f;
; #pragma unroll
;             for (int e = 0; e < 8; ++e) { y[e] = gbf[e] * (w0[e] * u0[e] + w1[e] * u1[e] + w2[e] * u2[e] + bc[e]); ss += y[e] * y[e]; }
;             const float rstd = 1.0f / sqrtf(wave_sum(ss) * (1.0f / 512.0f) + EPS);
;             u32x4 o;
;             o.x = cvtpk(y[0] * rstd * gc[0], y[1] * rstd * gc[1]); o.y = cvtpk(y[2] * rstd * gc[2], y[3] * rstd * gc[3]);
;             o.z = cvtpk(y[4] * rstd * gc[4], y[5] * rstd * gc[5]); o.w = cvtpk(y[6] * rstd * gc[6], y[7] * rstd * gc[7]);
;             *(GAS u32x4*)(YMIX + ((size_t)b * SEQ + s0 + r) * D + 512 + ch0) = o;
; #pragma unroll
;             for (int e = 0; e < 8; ++e) { u0[e] = u1[e]; u1[e] = u2[e]; }
	s_nop 1
	v_add_f32_dpp v5, v5, v5 row_mirror row_mask:0xf bank_mask:0xf
	ds_bpermute_b32 v78, v229, v5
	v_cvt_pk_bf16_f32 v94, v74, v75
	v_pk_mul_f32 v[74:75], v[120:121], v[0:1] op_sel_hi:[1,0]
	s_waitcnt vmcnt(7)
	v_lshlrev_b32_e32 v100, 16, v68
	v_pk_mul_f32 v[74:75], v[12:13], v[74:75]
	s_waitcnt lgkmcnt(0)
	v_add_f32_e32 v5, v5, v78
	ds_bpermute_b32 v78, v230, v5
	v_cvt_pk_bf16_f32 v95, v74, v75
	v_pk_mul_f32 v[74:75], v[118:119], v[0:1] op_sel_hi:[1,0]
	v_and_b32_e32 v101, 0xffff0000, v68
	v_pk_mul_f32 v[74:75], v[6:7], v[74:75]
	v_lshlrev_b32_e32 v68, 16, v60
	v_cvt_pk_bf16_f32 v96, v74, v75
	v_pk_mul_f32 v[74:75], v[102:103], v[0:1] op_sel_hi:[1,0]
	s_waitcnt lgkmcnt(0)
	v_add_f32_e32 v0, v5, v78
	v_fmamk_f32 v0, v0, 0x3b000000, v220
	v_mul_f32_e32 v5, 0x4f800000, v0
	v_cmp_gt_f32_e32 vcc, s45, v0
	v_pk_mul_f32 v[74:75], v[8:9], v[74:75]
	s_waitcnt vmcnt(6)
	v_and_b32_e32 v61, 0xffff0000, v64
	v_cndmask_b32_e32 v0, v0, v5, vcc
	v_sqrt_f32_e32 v5, v0
	v_cvt_pk_bf16_f32 v97, v74, v75
	v_add_co_u32_e64 v74, s[4:5], s47, v2
	v_add_u32_e32 v78, -1, v5
	s_nop 0
	v_addc_co_u32_e64 v75, s[4:5], 0, v3, s[4:5]
	v_fma_f32 v79, -v78, v5, v0
	v_cmp_ge_f32_e64 s[4:5], 0, v79
	v_add_u32_e32 v79, 1, v5
	v_pk_mul_f32 v[102:103], v[20:21], v[76:77]
	v_cndmask_b32_e64 v78, v5, v78, s[4:5]
	v_fma_f32 v5, -v79, v5, v0
	v_cmp_lt_f32_e64 s[4:5], 0, v5
	v_pk_fma_f32 v[88:89], v[16:17], v[88:89], v[102:103]
	v_lshlrev_b32_e32 v102, 16, v66
	v_cndmask_b32_e64 v5, v78, v79, s[4:5]
	v_mul_f32_e32 v78, 0x37800000, v5
	v_cndmask_b32_e32 v5, v5, v78, vcc
	v_lshlrev_b32_e32 v78, 16, v69
	v_and_b32_e32 v79, 0xffff0000, v69
	v_pk_mul_f32 v[98:99], v[78:79], v[98:99]
	v_lshlrev_b32_e32 v78, 16, v65
	v_and_b32_e32 v79, 0xffff0000, v65
	v_and_b32_e32 v69, 0xffff0000, v60
	v_lshlrev_b32_e32 v60, 16, v64
	v_pk_mul_f32 v[64:65], v[34:35], v[72:73]
	v_pk_mul_f32 v[68:69], v[100:101], v[68:69]
	v_pk_fma_f32 v[64:65], v[30:31], v[84:85], v[64:65]
	v_lshlrev_b32_e32 v84, 16, v67
	v_and_b32_e32 v85, 0xffff0000, v67
	v_lshlrev_b32_e32 v100, 16, v59
	v_and_b32_e32 v101, 0xffff0000, v59
	v_pk_mul_f32 v[84:85], v[84:85], v[100:101]
	v_lshlrev_b32_e32 v100, 16, v63
	v_and_b32_e32 v101, 0xffff0000, v63
	v_and_b32_e32 v103, 0xffff0000, v66
	v_lshlrev_b32_e32 v66, 16, v58
	v_and_b32_e32 v67, 0xffff0000, v58
	v_lshlrev_b32_e32 v58, 16, v62
	v_and_b32_e32 v59, 0xffff0000, v62
	v_pk_mul_f32 v[62:63], v[18:19], v[70:71]
	v_pk_mul_f32 v[66:67], v[102:103], v[66:67]
	v_pk_fma_f32 v[62:63], v[14:15], v[86:87], v[62:63]
	v_pk_fma_f32 v[88:89], v[24:25], v[84:85], v[88:89]
	v_pk_fma_f32 v[62:63], v[22:23], v[66:67], v[62:63]
	v_pk_add_f32 v[88:89], v[28:29], v[88:89]
	v_pk_add_f32 v[62:63], v[26:27], v[62:63]
	v_cmp_class_f32_e32 vcc, v0, v221
	v_pk_mul_f32 v[62:63], v[62:63], v[58:59]
	v_pk_fma_f32 v[64:65], v[38:39], v[68:69], v[64:65]
	v_pk_mul_f32 v[88:89], v[88:89], v[100:101]
	v_pk_mul_f32 v[58:59], v[62:63], v[62:63]
	v_cndmask_b32_e32 v0, v5, v0, vcc
	v_pk_add_f32 v[64:65], v[42:43], v[64:65]
	v_pk_mul_f32 v[100:101], v[88:89], v[88:89]
	v_add_f32_e32 v5, v58, v59
	v_pk_fma_f32 v[82:83], v[40:41], v[98:99], v[82:83]
	v_pk_mul_f32 v[64:65], v[64:65], v[60:61]
	v_add_f32_e32 v5, v100, v5
	v_pk_add_f32 v[82:83], v[44:45], v[82:83]
	v_pk_mul_f32 v[60:61], v[64:65], v[64:65]
	v_add_f32_e32 v5, v101, v5
	v_pk_mul_f32 v[78:79], v[82:83], v[78:79]
	v_add_f32_e32 v5, v60, v5
	v_pk_mul_f32 v[82:83], v[78:79], v[78:79]
	v_add_f32_e32 v5, v61, v5
	v_add_f32_e32 v5, v82, v5
	v_add_f32_e32 v5, v83, v5
	v_div_scale_f32 v59, s[4:5], v0, v0, 1.0
	v_rcp_f32_e32 v60, v59
	v_pk_mul_f32 v[36:37], v[36:37], v[98:99]
	s_waitcnt lgkmcnt(0)
	s_nop 1
	v_add_f32_dpp v5, v5, v5 quad_perm:[1,0,3,2] row_mask:0xf bank_mask:0xf
	v_fma_f32 v61, -v59, v60, 1.0
	v_fmac_f32_e32 v60, v61, v60
	v_div_scale_f32 v61, vcc, 1.0, v0, 1.0
	s_waitcnt lgkmcnt(0)
	s_nop 1
	v_add_f32_dpp v5, v5, v5 quad_perm:[2,3,0,1] row_mask:0xf bank_mask:0xf
	v_mul_f32_e32 v82, v61, v60
	v_fma_f32 v83, -v59, v82, v61
	v_fmac_f32_e32 v82, v83, v60
	v_fma_f32 v59, -v59, v82, v61
	s_waitcnt lgkmcnt(0)
	s_nop 1
	v_add_f32_dpp v5, v5, v5 row_half_mirror row_mask:0xf bank_mask:0xf
	v_div_fmas_f32 v58, v59, v60, v82
	v_div_fixup_f32 v0, v58, v0, 1.0
	v_pk_mul_f32 v[58:59], v[106:107], v[0:1] op_sel_hi:[1,0]
	s_waitcnt vmcnt(5)
	v_and_b32_e32 v83, 0xffff0000, v57
	s_waitcnt lgkmcnt(0)
	s_nop 1
	v_add_f32_dpp v5, v5, v5 row_mirror row_mask:0xf bank_mask:0xf
	ds_bpermute_b32 v82, v229, v5
	v_pk_mul_f32 v[60:61], v[104:105], v[0:1] op_sel_hi:[1,0]
	v_pk_mul_f32 v[58:59], v[10:11], v[58:59]
	v_pk_mul_f32 v[60:61], v[12:13], v[60:61]
	v_cvt_pk_bf16_f32 v58, v58, v59
	s_waitcnt lgkmcnt(0)
	v_add_f32_e32 v5, v5, v82
	ds_bpermute_b32 v82, v230, v5
	v_cvt_pk_bf16_f32 v59, v60, v61
	v_pk_mul_f32 v[60:61], v[80:81], v[0:1] op_sel_hi:[1,0]
	v_pk_mul_f32 v[80:81], v[92:93], v[0:1] op_sel_hi:[1,0]
	v_pk_mul_f32 v[60:61], v[6:7], v[60:61]
	s_waitcnt lgkmcnt(0)
; __device__ __forceinline__ unsigned cvtpk(float lo, float hi) { f32x2 v = {lo, hi}; bf16x2_t b = __builtin_convertvector(v, bf16x2_t); return __builtin_bit_cast(unsigned, b); }
; #define GAS __attribute__((address_space(1)))
; __device__ __forceinline__ float bf_lo(unsigned w) { return __uint_as_float(w << 16); }
; __device__ __forceinline__ float bf_hi(unsigned w) { return __uint_as_float(w & 0xffff0000u); }
; #define CV_U(dst, xv, gv) do { dst[0] = bf_lo(xv.x) * bf_lo(gv.x); dst[1] = bf_hi(xv.x) * bf_hi(gv.x); dst[2] = bf_lo(xv.y) * bf_lo(gv.y); dst[3] = bf_hi(xv.y) * bf_hi(gv.y); \
;         dst[4] = bf_lo(xv.z) * bf_lo(gv.z); dst[5] = bf_hi(xv.z) * bf_hi(gv.z); dst[6] = bf_lo(xv.w) * bf_lo(gv.w); dst[7] = bf_hi(xv.w) * bf_hi(gv.w); } while (0)
; __device__ __forceinline__ void conv_unit(const bf16* PROJ, bf16* YMIX, const float* w_conv, const float* b_conv, const float* g_conv, int b, int c, int wave, int lane_in) {
;     ...
;         for (int r = 0; r < 8; ++r) {
;             float u2[8]; CV_U(u2, xa[r + 2], ga[r + 2]);
;             const u32x4 gbv = gb[r];
;             float gbf[8] = {bf_lo(gbv.x), bf_hi(gbv.x), bf_lo(gbv.y), bf_hi(gbv.y), bf_lo(gbv.z), bf_hi(gbv.z), bf_lo(gbv.w), bf_hi(gbv.w)};
;             float y[8]; float ss = 0.f;
; #pragma unroll
;             for (int e = 0; e < 8; ++e) { y[e] = gbf[e] * (w0[e] * u0[e] + w1[e] * u1[e] + w2[e] * u2[e] + bc[e]); ss += y[e] * y[e]; }
;             const float rstd = 1.0f / sqrtf(wave_sum(ss) * (1.0f / 512.0f) + EPS);
;             u32x4 o;
;             o.x = cvtpk(y[0] * rstd * gc[0], y[1] * rstd * gc[1]); o.y = cvtpk(y[2] * rstd * gc[2], y[3] * rstd * gc[3]);
;             o.z = cvtpk(y[4] * rstd * gc[4], y[5] * rstd * gc[5]); o.w = cvtpk(y[6] * rstd * gc[6], y[7] * rstd * gc[7]);
;             *(GAS u32x4*)(YMIX + ((size_t)b * SEQ + s0 + r) * D + 512 + ch0) = o;
; #pragma unroll
;             for (int e = 0; e < 8; ++e) { u0[e] = u1[e]; u1[e] = u2[e]; }
; __global__ void __launch_bounds__(NWAVES * 64, 2) fwd_megakernel(Args a_unused) {
;     ...
;                 for (int uu = vcu * 4; uu < vcu * 4 + 4; ++uu)
	v_add_f32_e32 v5, v5, v82
	v_fmamk_f32 v5, v5, 0x3b000000, v220
	v_cvt_pk_bf16_f32 v60, v60, v61
	v_mul_f32_e32 v61, 0x4f800000, v5
	v_cmp_gt_f32_e32 vcc, s45, v5
	v_pk_mul_f32 v[80:81], v[8:9], v[80:81]
	v_pk_fma_f32 v[32:33], v[32:33], v[90:91], v[36:37]
	v_cndmask_b32_e32 v5, v5, v61, vcc
	v_sqrt_f32_e32 v82, v5
	v_cvt_pk_bf16_f32 v61, v80, v81
	v_pk_mul_f32 v[34:35], v[34:35], v[68:69]
	v_pk_mul_f32 v[20:21], v[20:21], v[84:85]
	v_add_u32_e32 v0, -1, v82
	v_fma_f32 v80, -v0, v82, v5
	v_cmp_ge_f32_e64 s[4:5], 0, v80
	v_add_u32_e32 v80, 1, v82
	v_fma_f32 v81, -v80, v82, v5
	v_cndmask_b32_e64 v0, v82, v0, s[4:5]
	v_cmp_lt_f32_e64 s[4:5], 0, v81
	v_and_b32_e32 v81, 0xffff0000, v49
	v_lshlrev_b32_e32 v82, 16, v57
	v_cndmask_b32_e64 v0, v0, v80, s[4:5]
	v_mul_f32_e32 v80, 0x37800000, v0
	v_cndmask_b32_e32 v0, v0, v80, vcc
	v_lshlrev_b32_e32 v80, 16, v49
	v_pk_mul_f32 v[80:81], v[82:83], v[80:81]
	v_pk_fma_f32 v[30:31], v[30:31], v[72:73], v[34:35]
	v_pk_fma_f32 v[32:33], v[40:41], v[80:81], v[32:33]
	v_lshlrev_b32_e32 v40, 16, v48
	v_pk_add_f32 v[32:33], v[44:45], v[32:33]
	v_and_b32_e32 v41, 0xffff0000, v48
	v_lshlrev_b32_e32 v44, 16, v56
	v_and_b32_e32 v45, 0xffff0000, v56
	v_pk_mul_f32 v[40:41], v[44:45], v[40:41]
	v_pk_fma_f32 v[16:17], v[16:17], v[76:77], v[20:21]
	v_pk_fma_f32 v[30:31], v[38:39], v[40:41], v[30:31]
	v_lshlrev_b32_e32 v38, 16, v47
	v_and_b32_e32 v39, 0xffff0000, v47
	v_lshlrev_b32_e32 v40, 16, v55
	v_and_b32_e32 v41, 0xffff0000, v55
	v_pk_mul_f32 v[38:39], v[40:41], v[38:39]
	v_pk_mul_f32 v[18:19], v[18:19], v[66:67]
	v_pk_fma_f32 v[16:17], v[24:25], v[38:39], v[16:17]
	v_lshlrev_b32_e32 v24, 16, v46
	v_pk_add_f32 v[16:17], v[28:29], v[16:17]
	v_and_b32_e32 v25, 0xffff0000, v46
	v_lshlrev_b32_e32 v28, 16, v54
	v_and_b32_e32 v29, 0xffff0000, v54
	v_pk_mul_f32 v[24:25], v[28:29], v[24:25]
	v_pk_fma_f32 v[14:15], v[14:15], v[70:71], v[18:19]
	s_waitcnt vmcnt(4)
	v_lshlrev_b32_e32 v28, 16, v50
	v_pk_fma_f32 v[14:15], v[22:23], v[24:25], v[14:15]
	v_and_b32_e32 v29, 0xffff0000, v50
	v_pk_add_f32 v[14:15], v[26:27], v[14:15]
	v_lshlrev_b32_e32 v40, 16, v51
	v_and_b32_e32 v41, 0xffff0000, v51
	v_pk_mul_f32 v[18:19], v[14:15], v[28:29]
	v_cmp_class_f32_e32 vcc, v5, v221
	v_pk_mul_f32 v[20:21], v[16:17], v[40:41]
	v_pk_mul_f32 v[14:15], v[18:19], v[18:19]
	v_cndmask_b32_e32 v0, v0, v5, vcc
	v_lshlrev_b32_e32 v44, 16, v52
	v_and_b32_e32 v45, 0xffff0000, v52
	v_pk_add_f32 v[30:31], v[42:43], v[30:31]
	v_pk_mul_f32 v[16:17], v[20:21], v[20:21]
	v_add_f32_e32 v5, v14, v15
	v_pk_mul_f32 v[30:31], v[30:31], v[44:45]
	v_add_f32_e32 v5, v16, v5
	v_lshlrev_b32_e32 v82, 16, v53
	v_and_b32_e32 v83, 0xffff0000, v53
	v_pk_mul_f32 v[34:35], v[30:31], v[30:31]
	v_add_f32_e32 v5, v17, v5
	v_pk_mul_f32 v[32:33], v[32:33], v[82:83]
	v_add_f32_e32 v5, v34, v5
	v_pk_mul_f32 v[36:37], v[32:33], v[32:33]
	v_add_f32_e32 v5, v35, v5
	v_add_f32_e32 v5, v36, v5
	v_add_f32_e32 v5, v37, v5
	v_div_scale_f32 v15, s[4:5], v0, v0, 1.0
	v_rcp_f32_e32 v16, v15
	global_store_dwordx4 v[74:75], v[94:97], off offset:1024
	s_waitcnt lgkmcnt(0)
	s_nop 1
	v_add_f32_dpp v5, v5, v5 quad_perm:[1,0,3,2] row_mask:0xf bank_mask:0xf
	v_fma_f32 v17, -v15, v16, 1.0
	v_fmac_f32_e32 v16, v17, v16
	v_div_scale_f32 v17, vcc, 1.0, v0, 1.0
	s_waitcnt lgkmcnt(0)
	s_nop 1
	v_add_f32_dpp v5, v5, v5 quad_perm:[2,3,0,1] row_mask:0xf bank_mask:0xf
	v_mul_f32_e32 v22, v17, v16
	v_fma_f32 v23, -v15, v22, v17
	v_fmac_f32_e32 v22, v23, v16
	v_fma_f32 v15, -v15, v22, v17
	s_waitcnt lgkmcnt(0)
	s_nop 1
	v_add_f32_dpp v5, v5, v5 row_half_mirror row_mask:0xf bank_mask:0xf
	v_div_fmas_f32 v14, v15, v16, v22
	v_div_fixup_f32 v0, v14, v0, 1.0
	v_pk_mul_f32 v[14:15], v[62:63], v[0:1] op_sel_hi:[1,0]
	global_store_dwordx4 v[74:75], v[58:61], off offset:3072
	s_waitcnt lgkmcnt(0)
	s_nop 1
	v_add_f32_dpp v5, v5, v5 row_mirror row_mask:0xf bank_mask:0xf
	ds_bpermute_b32 v22, v229, v5
	v_pk_mul_f32 v[16:17], v[88:89], v[0:1] op_sel_hi:[1,0]
	v_pk_mul_f32 v[14:15], v[10:11], v[14:15]
	v_pk_mul_f32 v[16:17], v[12:13], v[16:17]
	v_cvt_pk_bf16_f32 v14, v14, v15
	s_waitcnt lgkmcnt(0)
	v_add_f32_e32 v5, v5, v22
	ds_bpermute_b32 v22, v230, v5
	v_cvt_pk_bf16_f32 v15, v16, v17
	v_pk_mul_f32 v[16:17], v[64:65], v[0:1] op_sel_hi:[1,0]
	s_waitcnt lgkmcnt(0)
	v_add_f32_e32 v5, v5, v22
	v_pk_mul_f32 v[16:17], v[6:7], v[16:17]
	v_fmamk_f32 v5, v5, 0x3b000000, v220
	v_cvt_pk_bf16_f32 v16, v16, v17
	v_mul_f32_e32 v17, 0x4f800000, v5
	v_cmp_gt_f32_e32 vcc, s45, v5
	v_pk_mul_f32 v[22:23], v[78:79], v[0:1] op_sel_hi:[1,0]
	s_nop 0
	v_cndmask_b32_e32 v5, v5, v17, vcc
	v_sqrt_f32_e32 v24, v5
	v_pk_mul_f32 v[22:23], v[8:9], v[22:23]
	v_add_u32_e32 v0, -1, v24
	v_cvt_pk_bf16_f32 v17, v22, v23
	v_fma_f32 v22, -v0, v24, v5
	v_cmp_ge_f32_e64 s[4:5], 0, v22
	v_add_u32_e32 v22, 1, v24
	v_fma_f32 v23, -v22, v24, v5
	v_cndmask_b32_e64 v0, v24, v0, s[4:5]
	v_cmp_lt_f32_e64 s[4:5], 0, v23
	s_nop 1
	v_cndmask_b32_e64 v0, v0, v22, s[4:5]
	v_mul_f32_e32 v22, 0x37800000, v0
	v_cndmask_b32_e32 v0, v0, v22, vcc
	v_cmp_class_f32_e32 vcc, v5, v221
	s_nop 1
	v_cndmask_b32_e32 v0, v0, v5, vcc
	v_div_scale_f32 v5, s[4:5], v0, v0, 1.0
	v_rcp_f32_e32 v22, v5
	v_add_co_u32_e32 v2, vcc, s39, v2
	s_add_i32 s4, s10, 1
	s_nop 0
	v_addc_co_u32_e32 v3, vcc, 0, v3, vcc
	global_store_dwordx4 v[2:3], v[14:17], off offset:1024
	s_cmp_ge_i32 s10, s35
	s_mov_b32 s10, s4
	v_fma_f32 v14, -v5, v22, 1.0
	v_fmac_f32_e32 v22, v14, v22
	v_div_scale_f32 v14, vcc, 1.0, v0, 1.0
	v_mul_f32_e32 v15, v14, v22
	v_fma_f32 v16, -v5, v15, v14
	v_fmac_f32_e32 v15, v16, v22
	v_fma_f32 v5, -v5, v15, v14
	v_div_fmas_f32 v5, v5, v22, v15
	v_div_fixup_f32 v0, v5, v0, 1.0
	v_pk_mul_f32 v[14:15], v[18:19], v[0:1] op_sel_hi:[1,0]
	s_nop 0
	v_pk_mul_f32 v[10:11], v[10:11], v[14:15]
	v_pk_mul_f32 v[14:15], v[20:21], v[0:1] op_sel_hi:[1,0]
	v_cvt_pk_bf16_f32 v10, v10, v11
	v_pk_mul_f32 v[12:13], v[12:13], v[14:15]
	s_nop 0
	v_cvt_pk_bf16_f32 v11, v12, v13
	v_pk_mul_f32 v[12:13], v[30:31], v[0:1] op_sel_hi:[1,0]
	s_nop 0
	v_pk_mul_f32 v[6:7], v[6:7], v[12:13]
	s_nop 0
	v_cvt_pk_bf16_f32 v12, v6, v7
	v_pk_mul_f32 v[6:7], v[32:33], v[0:1] op_sel_hi:[1,0]
	s_nop 0
	v_pk_mul_f32 v[6:7], v[8:9], v[6:7]
	s_nop 0
	v_cvt_pk_bf16_f32 v13, v6, v7
	global_store_dwordx4 v[2:3], v[10:13], off offset:3072
	s_cbranch_scc1 .LBB0_546
